# window loop: next block's V fragments loaded in place chunk by chunk as soon as their PV MFMAs have issued (longer lead); top-k bisection starts at bit 29 (fewer than 16 values can reach 2.0)
# baseline (speedup 1.0000x reference)
.LBB0_1258:
	s_mov_b64 s[18:19], s[4:5]
	v_mov_b64_e32 v[34:35], v[16:17]
	v_mov_b64_e32 v[36:37], v[16:17]
	v_mov_b64_e32 v[38:39], v[16:17]
	v_mov_b64_e32 v[40:41], v[16:17]
	v_mov_b64_e32 v[42:43], v[16:17]
	v_mov_b64_e32 v[44:45], v[16:17]
	v_mov_b64_e32 v[46:47], v[16:17]
	v_mov_b64_e32 v[48:49], v[16:17]
	v_mov_b64_e32 v[50:51], v[16:17]
	v_mov_b64_e32 v[52:53], v[16:17]
	v_mov_b64_e32 v[54:55], v[16:17]
	v_mov_b64_e32 v[56:57], v[16:17]
	v_mov_b64_e32 v[58:59], v[16:17]
	v_mov_b64_e32 v[60:61], v[16:17]
	v_mov_b64_e32 v[62:63], v[16:17]
	v_mov_b64_e32 v[64:65], v[16:17]
	v_mov_b32_e32 v66, 0
	v_mov_b32_e32 v242, 0x3fb8aa3b
	ds_read_b128 v[68:71], v224
	ds_read_b128 v[72:75], v224 offset:32
	ds_read_b128 v[76:79], v224 offset:64
	ds_read_b128 v[80:83], v224 offset:96
	s_add_u32 s20, s18, 0x800000
	s_addc_u32 s21, s19, 0
	global_load_dwordx4 v[130:133], v194, s[20:21]
	global_load_dwordx4 v[146:149], v200, s[20:21]
	global_load_dwordx4 v[134:137], v194, s[20:21] offset:1024
	global_load_dwordx4 v[150:153], v202, s[20:21]
	global_load_dwordx4 v[138:141], v194, s[20:21] offset:2048
	global_load_dwordx4 v[154:157], v204, s[20:21]
	global_load_dwordx4 v[142:145], v194, s[20:21] offset:3072
	global_load_dwordx4 v[158:161], v206, s[20:21]
	s_waitcnt lgkmcnt(0)
.Lw_loop:
	s_add_u32 s20, s18, 0x802000
	s_addc_u32 s21, s19, 0
	s_cmp_lt_i32 s17, s96
	s_cbranch_scc0 .Lw_near
	s_cmp_eq_u32 s17, s15
	s_cbranch_scc1 .Lw_band
	s_waitcnt vmcnt(8)
	v_mfma_f32_32x32x16_bf16 v[162:177], v[98:101], v[68:71], 0
	v_mfma_f32_32x32x16_bf16 v[178:193], v[114:117], v[68:71], 0
	v_mfma_f32_32x32x16_bf16 v[162:177], v[102:105], v[72:75], v[162:177]
	v_mfma_f32_32x32x16_bf16 v[178:193], v[118:121], v[72:75], v[178:193]
	v_mfma_f32_32x32x16_bf16 v[162:177], v[106:109], v[76:79], v[162:177]
	v_mfma_f32_32x32x16_bf16 v[178:193], v[122:125], v[76:79], v[178:193]
	v_mfma_f32_32x32x16_bf16 v[162:177], v[110:113], v[80:83], v[162:177]
	v_mfma_f32_32x32x16_bf16 v[178:193], v[126:129], v[80:83], v[178:193]
	s_add_u32 s22, s18, 0x2000
	s_addc_u32 s23, s19, 0
	global_load_dwordx4 v[98:101], v194, s[22:23]
	global_load_dwordx4 v[102:105], v194, s[22:23] offset:1024
	global_load_dwordx4 v[106:109], v194, s[22:23] offset:2048
	global_load_dwordx4 v[110:113], v194, s[22:23] offset:3072
	global_load_dwordx4 v[114:117], v200, s[22:23]
	global_load_dwordx4 v[118:121], v202, s[22:23]
	global_load_dwordx4 v[122:125], v204, s[22:23]
	global_load_dwordx4 v[126:129], v206, s[22:23]
	s_nop 1
	v_max3_f32 v92, v162, v163, v164
	v_max3_f32 v92, v92, v165, v166
	v_max3_f32 v92, v92, v167, v168
	v_max3_f32 v92, v92, v169, v170
	v_max3_f32 v92, v92, v171, v172
	v_max3_f32 v92, v92, v173, v174
	v_max3_f32 v92, v92, v175, v176
	v_max3_f32 v92, v92, v177, v177
	v_max3_f32 v97, v178, v179, v180
	v_max3_f32 v97, v97, v181, v182
	v_max3_f32 v97, v97, v183, v184
	v_max3_f32 v97, v97, v185, v186
	v_max3_f32 v97, v97, v187, v188
	v_max3_f32 v97, v97, v189, v190
	v_max3_f32 v97, v97, v191, v192
	v_max3_f32 v97, v97, v193, v193
	v_max_f32_e32 v92, v92, v97
	v_fmamk_f32 v92, v92, 0x3fb8aa3b, v208
	v_mov_b32_e32 v93, v92
	s_nop 1
	v_permlane32_swap_b32_e32 v92, v93
	v_max3_f32 v97, v234, v92, v93
	v_cmp_neq_f32_e32 vcc, s68, v97
	s_nop 1
	v_cndmask_b32_e32 v94, 0, v97, vcc
	v_cmp_neq_f32_e32 vcc, v97, v234
	s_cbranch_vccz .Lw_nr_far
	v_sub_f32_e32 v96, v234, v94
	v_exp_f32_e32 v96, v96
	s_nop 0
	v_pk_mul_f32 v[34:35], v[34:35], v[96:97] op_sel_hi:[1,0]
	v_pk_mul_f32 v[36:37], v[36:37], v[96:97] op_sel_hi:[1,0]
	v_pk_mul_f32 v[38:39], v[38:39], v[96:97] op_sel_hi:[1,0]
	v_pk_mul_f32 v[40:41], v[40:41], v[96:97] op_sel_hi:[1,0]
	v_pk_mul_f32 v[42:43], v[42:43], v[96:97] op_sel_hi:[1,0]
	v_pk_mul_f32 v[44:45], v[44:45], v[96:97] op_sel_hi:[1,0]
	v_pk_mul_f32 v[46:47], v[46:47], v[96:97] op_sel_hi:[1,0]
	v_pk_mul_f32 v[48:49], v[48:49], v[96:97] op_sel_hi:[1,0]
	v_pk_mul_f32 v[50:51], v[50:51], v[96:97] op_sel_hi:[1,0]
	v_pk_mul_f32 v[52:53], v[52:53], v[96:97] op_sel_hi:[1,0]
	v_pk_mul_f32 v[54:55], v[54:55], v[96:97] op_sel_hi:[1,0]
	v_pk_mul_f32 v[56:57], v[56:57], v[96:97] op_sel_hi:[1,0]
	v_pk_mul_f32 v[58:59], v[58:59], v[96:97] op_sel_hi:[1,0]
	v_pk_mul_f32 v[60:61], v[60:61], v[96:97] op_sel_hi:[1,0]
	v_pk_mul_f32 v[62:63], v[62:63], v[96:97] op_sel_hi:[1,0]
	v_pk_mul_f32 v[64:65], v[64:65], v[96:97] op_sel_hi:[1,0]
	v_mul_f32_e32 v66, v96, v66
.Lw_nr_far:
	v_mov_b32_e32 v234, v97
	v_sub_f32_e32 v240, v208, v94
	v_pk_fma_f32 v[162:163], v[162:163], v[242:243], v[240:241] op_sel_hi:[1,0,0]
	v_pk_fma_f32 v[164:165], v[164:165], v[242:243], v[240:241] op_sel_hi:[1,0,0]
	v_pk_fma_f32 v[166:167], v[166:167], v[242:243], v[240:241] op_sel_hi:[1,0,0]
	v_pk_fma_f32 v[168:169], v[168:169], v[242:243], v[240:241] op_sel_hi:[1,0,0]
	v_exp_f32_e32 v162, v162
	v_exp_f32_e32 v163, v163
	v_exp_f32_e32 v164, v164
	v_exp_f32_e32 v165, v165
	v_exp_f32_e32 v166, v166
	v_exp_f32_e32 v167, v167
	v_exp_f32_e32 v168, v168
	v_exp_f32_e32 v169, v169
	v_pk_add_f32 v[236:237], v[162:163], v[164:165]
	v_pk_add_f32 v[236:237], v[236:237], v[166:167]
	v_pk_add_f32 v[236:237], v[236:237], v[168:169]
	v_cvt_pk_bf16_f32 v84, v162, v163
	v_cvt_pk_bf16_f32 v85, v164, v165
	v_cvt_pk_bf16_f32 v86, v166, v167
	v_cvt_pk_bf16_f32 v87, v168, v169
	v_pk_fma_f32 v[170:171], v[170:171], v[242:243], v[240:241] op_sel_hi:[1,0,0]
	v_pk_fma_f32 v[172:173], v[172:173], v[242:243], v[240:241] op_sel_hi:[1,0,0]
	v_pk_fma_f32 v[174:175], v[174:175], v[242:243], v[240:241] op_sel_hi:[1,0,0]
	v_pk_fma_f32 v[176:177], v[176:177], v[242:243], v[240:241] op_sel_hi:[1,0,0]
	s_waitcnt vmcnt(8)
	v_mfma_f32_32x32x16_bf16 v[34:49], v[130:133], v[84:87], v[34:49]
	v_mfma_f32_32x32x16_bf16 v[50:65], v[146:149], v[84:87], v[50:65]
	s_cmp_lt_i32 s17, s44
	s_cbranch_scc0 .Lw_far_nv0
	global_load_dwordx4 v[130:133], v194, s[20:21]
	global_load_dwordx4 v[146:149], v200, s[20:21]
.Lw_far_nv0:
	v_exp_f32_e32 v170, v170
	v_exp_f32_e32 v171, v171
	v_exp_f32_e32 v172, v172
	v_exp_f32_e32 v173, v173
	v_exp_f32_e32 v174, v174
	v_exp_f32_e32 v175, v175
	v_exp_f32_e32 v176, v176
	v_exp_f32_e32 v177, v177
	v_pk_add_f32 v[236:237], v[236:237], v[170:171]
	v_pk_add_f32 v[236:237], v[236:237], v[172:173]
	v_pk_add_f32 v[236:237], v[236:237], v[174:175]
	v_pk_add_f32 v[236:237], v[236:237], v[176:177]
	v_cvt_pk_bf16_f32 v88, v170, v171
	v_cvt_pk_bf16_f32 v89, v172, v173
	v_cvt_pk_bf16_f32 v90, v174, v175
	v_cvt_pk_bf16_f32 v91, v176, v177
	v_pk_fma_f32 v[178:179], v[178:179], v[242:243], v[240:241] op_sel_hi:[1,0,0]
	v_pk_fma_f32 v[180:181], v[180:181], v[242:243], v[240:241] op_sel_hi:[1,0,0]
	v_pk_fma_f32 v[182:183], v[182:183], v[242:243], v[240:241] op_sel_hi:[1,0,0]
	v_pk_fma_f32 v[184:185], v[184:185], v[242:243], v[240:241] op_sel_hi:[1,0,0]
	v_mfma_f32_32x32x16_bf16 v[34:49], v[134:137], v[88:91], v[34:49]
	v_mfma_f32_32x32x16_bf16 v[50:65], v[150:153], v[88:91], v[50:65]
	s_cmp_lt_i32 s17, s44
	s_cbranch_scc0 .Lw_far_nv1
	global_load_dwordx4 v[134:137], v194, s[20:21] offset:1024
	global_load_dwordx4 v[150:153], v202, s[20:21]
.Lw_far_nv1:
	v_exp_f32_e32 v178, v178
	v_exp_f32_e32 v179, v179
	v_exp_f32_e32 v180, v180
	v_exp_f32_e32 v181, v181
	v_exp_f32_e32 v182, v182
	v_exp_f32_e32 v183, v183
	v_exp_f32_e32 v184, v184
	v_exp_f32_e32 v185, v185
	v_pk_add_f32 v[236:237], v[236:237], v[178:179]
	v_pk_add_f32 v[236:237], v[236:237], v[180:181]
	v_pk_add_f32 v[236:237], v[236:237], v[182:183]
	v_pk_add_f32 v[236:237], v[236:237], v[184:185]
	v_cvt_pk_bf16_f32 v84, v178, v179
	v_cvt_pk_bf16_f32 v85, v180, v181
	v_cvt_pk_bf16_f32 v86, v182, v183
	v_cvt_pk_bf16_f32 v87, v184, v185
	v_pk_fma_f32 v[186:187], v[186:187], v[242:243], v[240:241] op_sel_hi:[1,0,0]
	v_pk_fma_f32 v[188:189], v[188:189], v[242:243], v[240:241] op_sel_hi:[1,0,0]
	v_pk_fma_f32 v[190:191], v[190:191], v[242:243], v[240:241] op_sel_hi:[1,0,0]
	v_pk_fma_f32 v[192:193], v[192:193], v[242:243], v[240:241] op_sel_hi:[1,0,0]
	v_mfma_f32_32x32x16_bf16 v[34:49], v[138:141], v[84:87], v[34:49]
	v_mfma_f32_32x32x16_bf16 v[50:65], v[154:157], v[84:87], v[50:65]
	s_cmp_lt_i32 s17, s44
	s_cbranch_scc0 .Lw_far_nv2
	global_load_dwordx4 v[138:141], v194, s[20:21] offset:2048
	global_load_dwordx4 v[154:157], v204, s[20:21]
.Lw_far_nv2:
	v_exp_f32_e32 v186, v186
	v_exp_f32_e32 v187, v187
	v_exp_f32_e32 v188, v188
	v_exp_f32_e32 v189, v189
	v_exp_f32_e32 v190, v190
	v_exp_f32_e32 v191, v191
	v_exp_f32_e32 v192, v192
	v_exp_f32_e32 v193, v193
	v_pk_add_f32 v[236:237], v[236:237], v[186:187]
	v_pk_add_f32 v[236:237], v[236:237], v[188:189]
	v_pk_add_f32 v[236:237], v[236:237], v[190:191]
	v_pk_add_f32 v[236:237], v[236:237], v[192:193]
	v_cvt_pk_bf16_f32 v88, v186, v187
	v_cvt_pk_bf16_f32 v89, v188, v189
	v_cvt_pk_bf16_f32 v90, v190, v191
	v_cvt_pk_bf16_f32 v91, v192, v193
	s_nop 1
	v_mfma_f32_32x32x16_bf16 v[34:49], v[142:145], v[88:91], v[34:49]
	v_mfma_f32_32x32x16_bf16 v[50:65], v[158:161], v[88:91], v[50:65]
	s_cmp_lt_i32 s17, s44
	s_cbranch_scc0 .Lw_far_nv3
	global_load_dwordx4 v[142:145], v194, s[20:21] offset:3072
	global_load_dwordx4 v[158:161], v206, s[20:21]
.Lw_far_nv3:
	v_add_f32_e32 v235, v236, v237
	v_add_f32_e32 v66, v66, v235
	s_branch .Lw_next

.Lw_nr_band:
	v_mov_b32_e32 v234, v97
	v_pk_add_f32 v[162:163], v[162:163], v[94:95] op_sel_hi:[1,0] neg_lo:[0,1] neg_hi:[0,1]
	v_pk_add_f32 v[164:165], v[164:165], v[94:95] op_sel_hi:[1,0] neg_lo:[0,1] neg_hi:[0,1]
	v_pk_add_f32 v[166:167], v[166:167], v[94:95] op_sel_hi:[1,0] neg_lo:[0,1] neg_hi:[0,1]
	v_pk_add_f32 v[168:169], v[168:169], v[94:95] op_sel_hi:[1,0] neg_lo:[0,1] neg_hi:[0,1]
	v_exp_f32_e32 v162, v162
	v_exp_f32_e32 v163, v163
	v_exp_f32_e32 v164, v164
	v_exp_f32_e32 v165, v165
	v_exp_f32_e32 v166, v166
	v_exp_f32_e32 v167, v167
	v_exp_f32_e32 v168, v168
	v_exp_f32_e32 v169, v169
	v_pk_add_f32 v[236:237], v[162:163], v[164:165]
	v_pk_add_f32 v[236:237], v[236:237], v[166:167]
	v_pk_add_f32 v[236:237], v[236:237], v[168:169]
	v_cvt_pk_bf16_f32 v84, v162, v163
	v_cvt_pk_bf16_f32 v85, v164, v165
	v_cvt_pk_bf16_f32 v86, v166, v167
	v_cvt_pk_bf16_f32 v87, v168, v169
	v_pk_add_f32 v[170:171], v[170:171], v[94:95] op_sel_hi:[1,0] neg_lo:[0,1] neg_hi:[0,1]
	v_pk_add_f32 v[172:173], v[172:173], v[94:95] op_sel_hi:[1,0] neg_lo:[0,1] neg_hi:[0,1]
	v_pk_add_f32 v[174:175], v[174:175], v[94:95] op_sel_hi:[1,0] neg_lo:[0,1] neg_hi:[0,1]
	v_pk_add_f32 v[176:177], v[176:177], v[94:95] op_sel_hi:[1,0] neg_lo:[0,1] neg_hi:[0,1]
	s_waitcnt vmcnt(8)
	v_mfma_f32_32x32x16_bf16 v[34:49], v[130:133], v[84:87], v[34:49]
	v_mfma_f32_32x32x16_bf16 v[50:65], v[146:149], v[84:87], v[50:65]
	s_cmp_lt_i32 s17, s44
	s_cbranch_scc0 .Lw_band_nv0
	global_load_dwordx4 v[130:133], v194, s[20:21]
	global_load_dwordx4 v[146:149], v200, s[20:21]
.Lw_band_nv0:
	v_exp_f32_e32 v170, v170
	v_exp_f32_e32 v171, v171
	v_exp_f32_e32 v172, v172
	v_exp_f32_e32 v173, v173
	v_exp_f32_e32 v174, v174
	v_exp_f32_e32 v175, v175
	v_exp_f32_e32 v176, v176
	v_exp_f32_e32 v177, v177
	v_pk_add_f32 v[236:237], v[236:237], v[170:171]
	v_pk_add_f32 v[236:237], v[236:237], v[172:173]
	v_pk_add_f32 v[236:237], v[236:237], v[174:175]
	v_pk_add_f32 v[236:237], v[236:237], v[176:177]
	v_cvt_pk_bf16_f32 v88, v170, v171
	v_cvt_pk_bf16_f32 v89, v172, v173
	v_cvt_pk_bf16_f32 v90, v174, v175
	v_cvt_pk_bf16_f32 v91, v176, v177
	v_pk_add_f32 v[178:179], v[178:179], v[94:95] op_sel_hi:[1,0] neg_lo:[0,1] neg_hi:[0,1]
	v_pk_add_f32 v[180:181], v[180:181], v[94:95] op_sel_hi:[1,0] neg_lo:[0,1] neg_hi:[0,1]
	v_pk_add_f32 v[182:183], v[182:183], v[94:95] op_sel_hi:[1,0] neg_lo:[0,1] neg_hi:[0,1]
	v_pk_add_f32 v[184:185], v[184:185], v[94:95] op_sel_hi:[1,0] neg_lo:[0,1] neg_hi:[0,1]
	v_mfma_f32_32x32x16_bf16 v[34:49], v[134:137], v[88:91], v[34:49]
	v_mfma_f32_32x32x16_bf16 v[50:65], v[150:153], v[88:91], v[50:65]
	s_cmp_lt_i32 s17, s44
	s_cbranch_scc0 .Lw_band_nv1
	global_load_dwordx4 v[134:137], v194, s[20:21] offset:1024
	global_load_dwordx4 v[150:153], v202, s[20:21]
.Lw_band_nv1:
	v_exp_f32_e32 v178, v178
	v_exp_f32_e32 v179, v179
	v_exp_f32_e32 v180, v180
	v_exp_f32_e32 v181, v181
	v_exp_f32_e32 v182, v182
	v_exp_f32_e32 v183, v183
	v_exp_f32_e32 v184, v184
	v_exp_f32_e32 v185, v185
	v_pk_add_f32 v[236:237], v[236:237], v[178:179]
	v_pk_add_f32 v[236:237], v[236:237], v[180:181]
	v_pk_add_f32 v[236:237], v[236:237], v[182:183]
	v_pk_add_f32 v[236:237], v[236:237], v[184:185]
	v_cvt_pk_bf16_f32 v84, v178, v179
	v_cvt_pk_bf16_f32 v85, v180, v181
	v_cvt_pk_bf16_f32 v86, v182, v183
	v_cvt_pk_bf16_f32 v87, v184, v185
	v_pk_add_f32 v[186:187], v[186:187], v[94:95] op_sel_hi:[1,0] neg_lo:[0,1] neg_hi:[0,1]
	v_pk_add_f32 v[188:189], v[188:189], v[94:95] op_sel_hi:[1,0] neg_lo:[0,1] neg_hi:[0,1]
	v_pk_add_f32 v[190:191], v[190:191], v[94:95] op_sel_hi:[1,0] neg_lo:[0,1] neg_hi:[0,1]
	v_pk_add_f32 v[192:193], v[192:193], v[94:95] op_sel_hi:[1,0] neg_lo:[0,1] neg_hi:[0,1]
	v_mfma_f32_32x32x16_bf16 v[34:49], v[138:141], v[84:87], v[34:49]
	v_mfma_f32_32x32x16_bf16 v[50:65], v[154:157], v[84:87], v[50:65]
	s_cmp_lt_i32 s17, s44
	s_cbranch_scc0 .Lw_band_nv2
	global_load_dwordx4 v[138:141], v194, s[20:21] offset:2048
	global_load_dwordx4 v[154:157], v204, s[20:21]

.Lw_near_pv:
	v_mfma_f32_32x32x16_bf16 v[34:49], v[130:133], v[84:87], v[34:49]
	v_mfma_f32_32x32x16_bf16 v[50:65], v[146:149], v[84:87], v[50:65]
	s_cmp_lt_i32 s17, s44
	s_cbranch_scc0 .Lw_near_nv0
	global_load_dwordx4 v[130:133], v194, s[20:21]
	global_load_dwordx4 v[146:149], v200, s[20:21]

.Lw_near_nv3:
	v_add_f32_e32 v235, v236, v237
	v_add_f32_e32 v66, v66, v235

.LBB0_1314:
	s_or_b32 s26, s4, s84
	v_lshl_add_u32 v13, s26, 9, v1
	v_mov_b32_e32 v3, 1
	v_mov_b32_e32 v2, 1
	v_mov_b32_e32 v6, 1
	v_mov_b32_e32 v7, 1
	v_mov_b32_e32 v4, 1
	v_mov_b32_e32 v5, 1
	v_mov_b32_e32 v10, 1
	v_mov_b32_e32 v11, 1
	s_and_saveexec_b64 s[24:25], s[18:19]
	ds_read_b32 v14, v13 offset:43008
	ds_read_b32 v15, v13 offset:43520
	ds_read_b32 v16, v13 offset:44032
	ds_read_b32 v17, v13 offset:44544
	s_or_b64 exec, exec, s[24:25]
	s_and_saveexec_b64 s[24:25], s[22:23]
	ds_read_b32 v18, v13 offset:43264
	ds_read_b32 v19, v13 offset:43776
	ds_read_b32 v20, v13 offset:44288
	ds_read_b32 v21, v13 offset:44800
	s_or_b64 exec, exec, s[24:25]
	s_waitcnt lgkmcnt(0)
	s_and_saveexec_b64 s[24:25], s[18:19]
	v_add_u32_e32 v3, 1, v14
	v_add_u32_e32 v6, 1, v15
	v_add_u32_e32 v4, 1, v16
	v_add_u32_e32 v10, 1, v17
	s_or_b64 exec, exec, s[24:25]
	s_and_saveexec_b64 s[24:25], s[22:23]
	v_add_u32_e32 v2, 1, v18
	v_add_u32_e32 v7, 1, v19
	v_add_u32_e32 v5, 1, v20
	v_add_u32_e32 v11, 1, v21
	s_or_b64 exec, exec, s[24:25]
	v_cndmask_b32_e64 v3, v3, v221, s[12:13]
	v_cndmask_b32_e64 v2, v2, v221, s[14:15]
	v_cndmask_b32_e64 v4, v4, v221, s[12:13]
	v_cndmask_b32_e64 v5, v5, v221, s[14:15]
	v_cndmask_b32_e64 v6, v6, v221, s[12:13]
	v_cndmask_b32_e64 v7, v7, v221, s[14:15]
	v_cndmask_b32_e64 v8, v3, 0, s[16:17]
	v_cndmask_b32_e64 v9, v2, 0, s[20:21]
	v_cndmask_b32_e64 v2, v10, v221, s[12:13]
	v_cndmask_b32_e64 v3, v11, v221, s[14:15]
	v_cndmask_b32_e64 v4, v4, 0, s[16:17]
	v_cndmask_b32_e64 v5, v5, 0, s[20:21]
	v_cndmask_b32_e64 v6, v6, 0, s[16:17]
	v_cndmask_b32_e64 v7, v7, 0, s[20:21]
	v_cndmask_b32_e64 v2, v2, 0, s[16:17]
	v_cndmask_b32_e64 v3, v3, 0, s[20:21]
	s_mov_b32 s97, 1
	s_andn2_b64 vcc, exec, s[46:47]
	s_mov_b32 s74, 1
	s_mov_b32 s75, 1
	s_mov_b32 s54, 1
	s_cbranch_vccnz .LBB0_1333
	s_mov_b32 s50, 29
	s_mov_b32 s54, 0
	s_mov_b32 s75, 0
	s_mov_b32 s74, 0
	s_mov_b32 s97, 0
	s_mov_b32 s51, 0
